# k13: k12 + retention side-unit top wait removed (loads overlap the previous unit's store drain)
# speedup vs baseline: 1.0017x; 1.0016x over previous
; template <int TYPE>
; __device__ __forceinline__ void mix_sg_unit(Frame& F, int b, int h, int mode  , const float* rot) {
;     ...
;     f32x4 S[8]; f32x4 nacc = {0.f, 0.f, 0.f, 0.f}; float m0 = 0.f;
; #pragma unroll
;     for (int mt = 0; mt < 8; ++mt) S[mt] = (f32x4){0.f, 0.f, 0.f, 0.f};
; __device__ __forceinline__ void mixer_layer0(Frame& F) {
;     ...
;     for (int u = bid - 64; u < 1024 + 8; u += F.G - 64) {
;         int ty, bh, mode;
;         if (u < 1024) { ty = u >> 9; bh = u & 511; mode = 1; } else { ty = (u - 1024) >> 2; bh = (u - 1024) & 3; mode = 2; }
;         if (ty == 0) mix_sg_unit<0>(F, bh >> 2, bh & 3, mode, rot); else mix_sg_unit<1>(F, bh >> 2, bh & 3, mode, rot);
.LBB0_720:
	s_cmpk_lt_i32 s43, 0x400
	s_cselect_b64 s[0:1], -1, 0
	v_cndmask_b32_e64 v0, 0, 1, s[0:1]
	s_add_i32 s0, s43, 0xfffffc00
	s_lshr_b32 s34, s0, 2
	s_ashr_i32 s35, s43, 9
	s_cmpk_gt_i32 s43, 0x3ff
	s_cselect_b64 s[0:1], -1, 0
	s_and_b64 s[28:29], s[0:1], exec
	s_cselect_b32 s28, 3, 0x1ff
	s_cselect_b32 s29, s34, s35
	s_and_b32 s56, s28, s43
	s_cmp_lg_u32 s29, 0
	v_cmp_ne_u32_e64 s[28:29], 1, v0
	s_cbranch_scc0 .LBB0_726
	v_mov_b32_e32 v16, 0
	s_lshr_b32 s57, s56, 2
	s_and_b32 s58, s43, 3
	s_and_b64 vcc, exec, s[28:29]
	v_mov_b32_e32 v17, v16
	v_mov_b32_e32 v18, v16
	v_mov_b32_e32 v19, v16
	v_mov_b32_e32 v12, v16
	v_mov_b32_e32 v13, v16
	v_mov_b32_e32 v14, v16
	v_mov_b32_e32 v15, v16
	v_mov_b32_e32 v20, v16
	v_mov_b32_e32 v21, v16
	v_mov_b32_e32 v22, v16
	v_mov_b32_e32 v23, v16
	v_mov_b32_e32 v24, v16
	v_mov_b32_e32 v25, v16
	v_mov_b32_e32 v26, v16
	v_mov_b32_e32 v27, v16
	v_mov_b32_e32 v36, v16
	v_mov_b32_e32 v37, v16
	v_mov_b32_e32 v38, v16
	v_mov_b32_e32 v39, v16
	v_mov_b32_e32 v28, v16
	v_mov_b32_e32 v29, v16
	v_mov_b32_e32 v30, v16
	v_mov_b32_e32 v31, v16
	v_mov_b32_e32 v32, v16
	v_mov_b32_e32 v33, v16
	v_mov_b32_e32 v34, v16
	v_mov_b32_e32 v35, v16
	v_mov_b32_e32 v40, v16
	v_mov_b32_e32 v41, v16
	v_mov_b32_e32 v42, v16
	v_mov_b32_e32 v43, v16
	s_cbranch_vccnz .LBB0_723
